# v8 + attention: next unit K1/K2 tiles and Q fragments requested during the current unit final step
# speedup vs baseline: 1.0056x; 1.0056x over previous
.LBB0_828:
	s_lshr_b32 s1, s0, 1
	s_or_b32 s1, s1, s3
	s_and_b32 s4, s0, 1
	s_sub_i32 s6, 15, s1
	s_cmp_eq_u32 s4, 0
	s_cselect_b64 s[56:57], -1, 0
	s_and_b64 s[4:5], s[56:57], exec
	s_cselect_b32 s1, s1, s6
	s_lshl_b32 s13, s1, 8
	s_add_u32 s54, s75, s13
	s_addc_u32 s55, s79, 0
	s_mul_i32 s4, s55, 0x600
	s_mul_hi_u32 s5, s54, 0x600
	v_ashrrev_i32_e32 v206, 5, v204
	s_add_i32 s5, s5, s4
	s_mul_i32 s4, s54, 0x600
	v_readfirstlane_b32 s6, v200
	v_and_b32_e32 v205, 31, v204
	s_add_u32 s4, s81, s4
	s_mov_b32 m0, s6
	s_nop 0
	global_load_lds_dwordx4 v216, s[18:19]
	v_readfirstlane_b32 s6, v201
	v_lshlrev_b32_e32 v2, 3, v206
	s_addc_u32 s5, s82, s5
	s_add_i32 s7, s6, s91
	v_mul_u32_u24_e32 v0, 0x300, v205
	v_ashrrev_i32_e32 v3, 31, v2
	s_cmp_lg_u32 s0, 0
	s_cbranch_scc1 .Latt_skip0
	s_mov_b32 m0, s7
	s_nop 0
	global_load_lds_dwordx4 v216, s[20:21]
.Latt_skip0:
	v_readfirstlane_b32 s7, v202
	v_lshl_add_u64 v[2:3], v[2:3], 1, s[4:5]
	v_lshlrev_b32_e32 v0, 1, v0
	s_add_i32 s10, s7, s91
	s_cmp_lg_u32 s0, 0
	s_cbranch_scc1 .Latt_skip1
	s_mov_b32 m0, s10
	s_nop 0
	global_load_lds_dwordx4 v216, s[30:31]
.Latt_skip1:
	v_lshl_add_u64 v[2:3], v[2:3], 0, v[0:1]
	s_cmp_lg_u32 s0, 0
	s_cbranch_scc1 .Latt_skip2
	global_load_dwordx4 v[176:179], v[2:3], off
	global_load_dwordx4 v[168:171], v[2:3], off offset:32
	global_load_dwordx4 v[164:167], v[2:3], off offset:64
	s_waitcnt lgkmcnt(0)
	global_load_dwordx4 v[156:159], v[2:3], off offset:96
	global_load_dwordx4 v[148:151], v[2:3], off offset:128
	global_load_dwordx4 v[144:147], v[2:3], off offset:160
.Latt_skip2:
	v_mov_b64_e32 v[46:47], v[30:31]
	v_mov_b64_e32 v[44:45], v[28:29]
	v_mov_b64_e32 v[42:43], v[26:27]
	v_mov_b64_e32 v[40:41], v[24:25]
	v_mov_b64_e32 v[38:39], v[22:23]
	v_mov_b64_e32 v[36:37], v[20:21]
	v_mov_b64_e32 v[34:35], v[18:19]
	v_mov_b64_e32 v[32:33], v[16:17]
	s_add_i32 s6, s6, s92
	s_cmp_lg_u32 s0, 0
	s_cbranch_scc1 .Latt_skip3
	s_mov_b32 m0, s6
	s_nop 0
	global_load_lds_dwordx4 v216, s[34:35]
.Latt_skip3:
	v_lshlrev_b32_e32 v0, 10, v206
	v_lshlrev_b32_e32 v4, 4, v205
	s_add_i32 s7, s7, s92
	s_cmp_lg_u32 s0, 0
	s_cbranch_scc1 .Latt_skip4
	s_mov_b32 m0, s7
	s_nop 0
	global_load_lds_dwordx4 v216, s[36:37]
.Latt_skip4:
	v_add3_u32 v214, 0, v0, v4
	s_waitcnt vmcnt(5) lgkmcnt(0)
	s_barrier
	ds_read_b128 v[2:5], v214
	ds_read_b128 v[6:9], v214 offset:512
	s_cmp_lg_u32 s1, 0
	s_cselect_b64 s[4:5], -1, 0
	v_lshlrev_b32_e32 v212, 2, v206
	v_or_b32_e32 v213, s74, v205
	s_and_b64 vcc, exec, s[4:5]
	s_waitcnt vmcnt(5) lgkmcnt(1)
	v_mfma_f32_32x32x16_bf16 v[48:63], v[2:5], v[176:179], v[32:47]
	s_waitcnt lgkmcnt(0)
	v_mfma_f32_32x32x16_bf16 v[32:47], v[6:9], v[176:179], v[32:47]
	ds_read_b128 v[2:5], v214 offset:2048
	ds_read_b128 v[6:9], v214 offset:2560
	s_waitcnt vmcnt(4) lgkmcnt(1)
	v_mfma_f32_32x32x16_bf16 v[48:63], v[2:5], v[168:171], v[48:63]
	s_waitcnt lgkmcnt(0)
	v_mfma_f32_32x32x16_bf16 v[32:47], v[6:9], v[168:171], v[32:47]
	ds_read_b128 v[2:5], v214 offset:4096
	ds_read_b128 v[6:9], v214 offset:4608
	s_waitcnt vmcnt(3) lgkmcnt(1)
	v_mfma_f32_32x32x16_bf16 v[48:63], v[2:5], v[164:167], v[48:63]
	s_waitcnt lgkmcnt(0)
	v_mfma_f32_32x32x16_bf16 v[32:47], v[6:9], v[164:167], v[32:47]
	ds_read_b128 v[2:5], v214 offset:6144
	ds_read_b128 v[6:9], v214 offset:6656
	s_waitcnt vmcnt(2) lgkmcnt(1)
	v_mfma_f32_32x32x16_bf16 v[48:63], v[2:5], v[156:159], v[48:63]
	s_waitcnt lgkmcnt(0)
	v_mfma_f32_32x32x16_bf16 v[32:47], v[6:9], v[156:159], v[32:47]
	ds_read_b128 v[2:5], v214 offset:8192
	ds_read_b128 v[6:9], v214 offset:8704
	s_waitcnt vmcnt(1) lgkmcnt(1)
	v_mfma_f32_32x32x16_bf16 v[48:63], v[2:5], v[148:151], v[48:63]
	s_waitcnt lgkmcnt(0)
	v_mfma_f32_32x32x16_bf16 v[32:47], v[6:9], v[148:151], v[32:47]
	ds_read_b128 v[2:5], v214 offset:10240
	ds_read_b128 v[6:9], v214 offset:10752
	s_waitcnt vmcnt(0) lgkmcnt(1)
	v_mfma_f32_32x32x16_bf16 v[48:63], v[2:5], v[144:147], v[48:63]
	s_waitcnt lgkmcnt(0)
	v_mfma_f32_32x32x16_bf16 v[32:47], v[6:9], v[144:147], v[32:47]
	s_nop 15
	s_nop 7
	s_cbranch_vccnz .LBB0_830
	v_subrev_u32_e32 v0, s13, v212
	v_add_u32_e32 v2, 32, v0
	v_cmp_le_i32_e32 vcc, v2, v213
	v_add_u32_e32 v2, 33, v0
	s_nop 6
	v_cndmask_b32_e32 v32, v203, v32, vcc
	v_cmp_lt_i32_e32 vcc, v0, v213
	s_nop 1
	v_cndmask_b32_e32 v49, v203, v49, vcc
	v_cmp_le_i32_e32 vcc, v0, v213
	s_nop 1
	v_cndmask_b32_e32 v48, v203, v48, vcc
	v_cmp_le_i32_e32 vcc, v2, v213
	v_or_b32_e32 v2, 2, v212
	s_nop 0
	v_cndmask_b32_e32 v33, v203, v33, vcc
	v_cmp_le_i32_e32 vcc, v2, v213
	v_add_u32_e32 v2, 34, v0
	s_nop 0
	v_cndmask_b32_e32 v50, v203, v50, vcc
	v_cmp_le_i32_e32 vcc, v2, v213
	v_or_b32_e32 v2, 3, v212
	s_nop 0
	v_cndmask_b32_e32 v34, v203, v34, vcc
	v_cmp_le_i32_e32 vcc, v2, v213
	v_add_u32_e32 v2, 35, v0
	s_nop 0
	v_cndmask_b32_e32 v51, v203, v51, vcc
	v_cmp_le_i32_e32 vcc, v2, v213
	v_add_u32_e32 v2, 8, v0
	s_nop 0
	v_cndmask_b32_e32 v35, v203, v35, vcc
	v_cmp_le_i32_e32 vcc, v2, v213
	v_add_u32_e32 v2, 40, v0
	s_nop 0
	v_cndmask_b32_e32 v52, v203, v52, vcc
	v_cmp_le_i32_e32 vcc, v2, v213
	v_add_u32_e32 v2, 9, v0
	s_nop 0
	v_cndmask_b32_e32 v36, v203, v36, vcc
	v_cmp_le_i32_e32 vcc, v2, v213
	v_add_u32_e32 v2, 41, v0
	s_nop 0
	v_cndmask_b32_e32 v53, v203, v53, vcc
	v_cmp_le_i32_e32 vcc, v2, v213
	v_add_u32_e32 v2, 10, v0
	s_nop 0
	v_cndmask_b32_e32 v37, v203, v37, vcc
	v_cmp_le_i32_e32 vcc, v2, v213
	v_add_u32_e32 v2, 42, v0
	s_nop 0
	v_cndmask_b32_e32 v54, v203, v54, vcc
	v_cmp_le_i32_e32 vcc, v2, v213
	v_add_u32_e32 v2, 11, v0
	s_nop 0
	v_cndmask_b32_e32 v38, v203, v38, vcc
	v_cmp_le_i32_e32 vcc, v2, v213
	v_add_u32_e32 v2, 43, v0
	s_nop 0
	v_cndmask_b32_e32 v55, v203, v55, vcc
	v_cmp_le_i32_e32 vcc, v2, v213
	v_add_u32_e32 v2, 16, v0
	s_nop 0
	v_cndmask_b32_e32 v39, v203, v39, vcc
	v_cmp_le_i32_e32 vcc, v2, v213
	v_add_u32_e32 v2, 48, v0
	s_nop 0
	v_cndmask_b32_e32 v56, v203, v56, vcc
	v_cmp_le_i32_e32 vcc, v2, v213
	v_add_u32_e32 v2, 17, v0
	s_nop 0
	v_cndmask_b32_e32 v40, v203, v40, vcc
	v_cmp_le_i32_e32 vcc, v2, v213
	v_add_u32_e32 v2, 49, v0
	s_nop 0
	v_cndmask_b32_e32 v57, v203, v57, vcc
	v_cmp_le_i32_e32 vcc, v2, v213
	v_add_u32_e32 v2, 18, v0
	s_nop 0
	v_cndmask_b32_e32 v41, v203, v41, vcc
	v_cmp_le_i32_e32 vcc, v2, v213
	v_add_u32_e32 v2, 50, v0
	s_nop 0
	v_cndmask_b32_e32 v58, v203, v58, vcc
	v_cmp_le_i32_e32 vcc, v2, v213
	v_add_u32_e32 v2, 19, v0
	s_nop 0
	v_cndmask_b32_e32 v42, v203, v42, vcc
	v_cmp_le_i32_e32 vcc, v2, v213
	v_add_u32_e32 v2, 51, v0
	s_nop 0
	v_cndmask_b32_e32 v59, v203, v59, vcc
	v_cmp_le_i32_e32 vcc, v2, v213
	v_add_u32_e32 v2, 24, v0
	s_nop 0
	v_cndmask_b32_e32 v43, v203, v43, vcc
	v_cmp_le_i32_e32 vcc, v2, v213
	v_add_u32_e32 v2, 56, v0
	s_nop 0
	v_cndmask_b32_e32 v60, v203, v60, vcc
	v_cmp_le_i32_e32 vcc, v2, v213
	v_add_u32_e32 v2, 25, v0
	s_nop 0
	v_cndmask_b32_e32 v44, v203, v44, vcc
	v_cmp_le_i32_e32 vcc, v2, v213
	v_add_u32_e32 v2, 57, v0
	s_nop 0
	v_cndmask_b32_e32 v61, v203, v61, vcc
	v_cmp_le_i32_e32 vcc, v2, v213
	v_add_u32_e32 v2, 26, v0
	s_nop 0
	v_cndmask_b32_e32 v45, v203, v45, vcc
	v_cmp_le_i32_e32 vcc, v2, v213
	v_add_u32_e32 v2, 58, v0
	s_nop 0
	v_cndmask_b32_e32 v62, v203, v62, vcc
	v_cmp_le_i32_e32 vcc, v2, v213
	v_add_u32_e32 v2, 27, v0
	v_add_u32_e32 v0, 59, v0
	v_cndmask_b32_e32 v46, v203, v46, vcc
	v_cmp_le_i32_e32 vcc, v2, v213
	s_nop 1
	v_cndmask_b32_e32 v63, v203, v63, vcc
	v_cmp_le_i32_e32 vcc, v0, v213
	s_nop 1
	v_cndmask_b32_e32 v47, v203, v47, vcc

.LBB0_898:
	s_mov_b32 s100, 0
	s_add_i32 s1, s0, 1
	s_lshr_b32 s4, s1, 1
	s_add_i32 s6, s4, s3
	s_sub_i32 s7, 15, s6
	s_and_b64 s[4:5], s[56:57], exec
	s_cselect_b32 s4, s7, s6
	s_cmp_lg_u32 s0, 7
	s_cselect_b32 s0, s4, -1
	s_cmp_lt_i32 s0, 0
	s_cbranch_scc1 .LBB0_900
	s_mov_b32 m0, s78
	s_nop 0
	global_load_lds_dwordx4 v216, s[14:15]
	s_lshl_b32 s0, s0, 8
	s_mov_b32 m0, s85
	s_nop 0
	global_load_lds_dwordx4 v216, s[16:17]
	s_add_u32 s0, s75, s0
	s_addc_u32 s4, s79, 0
	s_mulk_i32 s4, 0x600
	s_mul_hi_u32 s5, s0, 0x600
	s_add_i32 s5, s5, s4
	s_mulk_i32 s0, 0x600
	s_add_u32 s4, s81, s0
	v_lshrrev_b32_e32 v0, 1, v204
	s_movk_i32 s0, 0x600
	s_addc_u32 s5, s82, s5
	s_mov_b64 s[98:99], s[4:5]
	s_mov_b32 s100, 1
	v_mul_lo_u32 v0, v0, s0
	s_lshl_b32 s0, s76, 11
	s_add_i32 s0, s0, 0
	v_lshlrev_b32_e32 v2, 6, v204
	s_add_i32 s6, s0, 0x1a800
	v_and_or_b32 v0, v2, 64, v0
	s_mov_b32 m0, s6
	s_nop 0
	global_load_lds_dwordx4 v0, s[4:5]
	s_add_u32 s4, s4, 0x70
	s_addc_u32 s5, s5, 0
	s_add_i32 s0, s0, 0x1ac00
	s_mov_b32 m0, s0
	s_nop 0
	global_load_lds_dwordx4 v0, s[4:5]
	s_add_i32 m0, s78, 0x3000
	s_nop 0
	global_load_lds_dwordx4 v216, s[20:21]
	s_add_i32 m0, s85, 0x3000
	s_nop 0
	global_load_lds_dwordx4 v216, s[30:31]
	s_add_i32 m0, s78, 0x6000
	s_nop 0
	global_load_lds_dwordx4 v216, s[34:35]
	s_add_i32 m0, s85, 0x6000
	s_nop 0
	global_load_lds_dwordx4 v216, s[36:37]
.LBB0_900:
	ds_read_b128 v[2:5], v214 offset:40960
	v_add_u32_e32 v0, s22, v217
	s_waitcnt lgkmcnt(4)
	v_mfma_f32_32x32x16_bf16 v[112:127], v[196:199], v[176:179], v[64:79]
	v_add_f32_e32 v6, v96, v97
	v_add_f32_e32 v6, v98, v6
	v_add_f32_e32 v6, v99, v6
	v_add_f32_e32 v10, v100, v6
	v_cvt_pk_bf16_f32 v180, v96, v97
	ds_read_b128 v[6:9], v214 offset:41472
	s_waitcnt lgkmcnt(4)
	v_mfma_f32_32x32x16_bf16 v[64:79], v[184:187], v[176:179], v[64:79]
	v_add_f32_e32 v10, v101, v10
	v_add_f32_e32 v10, v102, v10
	v_add_f32_e32 v14, v103, v10
	v_cvt_pk_bf16_f32 v181, v98, v99
	ds_read_b128 v[10:13], v214 offset:43008
	s_waitcnt lgkmcnt(4)
	v_mfma_f32_32x32x16_bf16 v[112:127], v[188:191], v[168:171], v[112:127]
	v_add_f32_e32 v14, v104, v14
	v_add_f32_e32 v14, v105, v14
	v_add_f32_e32 v14, v106, v14
	v_cvt_pk_bf16_f32 v182, v100, v101
	ds_read_b128 v[96:99], v214 offset:43520
	s_waitcnt lgkmcnt(4)
	v_mfma_f32_32x32x16_bf16 v[64:79], v[192:195], v[168:171], v[64:79]
	v_add_f32_e32 v14, v107, v14
	v_add_f32_e32 v14, v108, v14
	v_add_f32_e32 v14, v109, v14
	v_cvt_pk_bf16_f32 v183, v102, v103
	ds_read_b128 v[100:103], v214 offset:45056
	s_waitcnt lgkmcnt(4)
	v_mfma_f32_32x32x16_bf16 v[112:127], v[2:5], v[164:167], v[112:127]
	v_add_f32_e32 v14, v110, v14
	v_add_f32_e32 v14, v111, v14
	v_add_f32_e32 v14, v80, v14
	v_cvt_pk_bf16_f32 v172, v104, v105
	ds_read_b128 v[2:5], v214 offset:45568
	s_waitcnt lgkmcnt(4)
	v_mfma_f32_32x32x16_bf16 v[64:79], v[6:9], v[164:167], v[64:79]
	v_add_f32_e32 v14, v81, v14
	v_add_f32_e32 v14, v82, v14
	v_add_f32_e32 v14, v83, v14
	v_cvt_pk_bf16_f32 v173, v106, v107
	ds_read_b128 v[104:107], v214 offset:47104
	s_waitcnt lgkmcnt(4)
	v_mfma_f32_32x32x16_bf16 v[112:127], v[10:13], v[156:159], v[112:127]
	v_add_f32_e32 v6, v84, v14
	v_add_f32_e32 v6, v85, v6
	v_cvt_pk_bf16_f32 v174, v108, v109
	v_cvt_pk_bf16_f32 v175, v110, v111
	ds_read_b128 v[108:111], v214 offset:47616
	s_waitcnt lgkmcnt(4)
	v_mfma_f32_32x32x16_bf16 v[64:79], v[96:99], v[156:159], v[64:79]
	v_add_f32_e32 v6, v86, v6
	v_add_f32_e32 v6, v87, v6
	v_cvt_pk_bf16_f32 v160, v80, v81
	v_cvt_pk_bf16_f32 v161, v82, v83
	ds_read_b64_tr_b16 v[128:129], v0 offset:49152
	ds_read_b64_tr_b16 v[130:131], v0 offset:49664
	s_waitcnt lgkmcnt(5)
	v_mfma_f32_32x32x16_bf16 v[112:127], v[100:103], v[148:151], v[112:127]
	v_add_f32_e32 v6, v88, v6
	v_add_f32_e32 v6, v89, v6
	v_cvt_pk_bf16_f32 v162, v84, v85
	v_cvt_pk_bf16_f32 v163, v86, v87
	ds_read_b64_tr_b16 v[10:11], v0 offset:53248
	ds_read_b64_tr_b16 v[12:13], v0 offset:53760
	s_waitcnt lgkmcnt(6)
	v_mfma_f32_32x32x16_bf16 v[64:79], v[2:5], v[148:151], v[64:79]
	v_add_f32_e32 v6, v90, v6
	v_add_f32_e32 v14, v91, v6
	v_cvt_pk_bf16_f32 v152, v88, v89
	v_cvt_pk_bf16_f32 v153, v90, v91
	ds_read_b64_tr_b16 v[6:7], v0 offset:50176
	ds_read_b64_tr_b16 v[8:9], v0 offset:50688
	s_waitcnt lgkmcnt(7)
	v_mfma_f32_32x32x16_bf16 v[112:127], v[104:107], v[144:147], v[112:127]
	v_add_f32_e32 v2, v92, v14
	v_add_f32_e32 v14, v93, v2
	v_cvt_pk_bf16_f32 v154, v92, v93
	ds_read_b64_tr_b16 v[2:3], v0 offset:54272
	ds_read_b64_tr_b16 v[4:5], v0 offset:54784
	s_waitcnt lgkmcnt(8)
	v_mfma_f32_32x32x16_bf16 v[64:79], v[108:111], v[144:147], v[64:79]
	v_add_f32_e32 v14, v94, v14
	v_add_f32_e32 v14, v95, v14
	v_cvt_pk_bf16_f32 v155, v94, v95
	s_cmp_eq_u32 s100, 0
	s_cbranch_scc1 .Latt_q_nopf
	v_lshrrev_b32_e32 v252, 5, v204
	v_lshlrev_b32_e32 v252, 4, v252
	v_and_b32_e32 v254, 31, v204
	v_mul_u32_u24_e32 v254, 0x600, v254
	v_add_u32_e32 v252, v252, v254
	v_mov_b32_e32 v253, 0
	v_lshl_add_u64 v[252:253], s[98:99], 0, v[252:253]
	global_load_dwordx4 v[176:179], v[252:253], off
	global_load_dwordx4 v[168:171], v[252:253], off offset:32
	global_load_dwordx4 v[164:167], v[252:253], off offset:64
	global_load_dwordx4 v[156:159], v[252:253], off offset:96
	global_load_dwordx4 v[148:151], v[252:253], off offset:128
	global_load_dwordx4 v[144:147], v[252:253], off offset:160
.Latt_q_nopf:
	v_add_u32_e32 v80, 0xe0, v212
	v_add_u32_e32 v15, 0xc0, v212
	v_cmp_le_i32_e32 vcc, v80, v213
	s_nop 5
	v_cndmask_b32_e32 v64, v203, v64, vcc
	v_cmp_lt_i32_e32 vcc, v15, v213
	s_nop 1
	v_cndmask_b32_e32 v81, v203, v113, vcc
	v_cmp_le_i32_e32 vcc, v15, v213
	v_add_u32_e32 v15, 0xe1, v212
	s_nop 0
	v_cndmask_b32_e32 v80, v203, v112, vcc
	v_cmp_le_i32_e32 vcc, v15, v213
	v_add_u32_e32 v15, 0xc2, v212
	v_max_f32_e32 v96, v80, v80
	v_cndmask_b32_e32 v65, v203, v65, vcc
	v_cmp_le_i32_e32 vcc, v15, v213
	v_add_u32_e32 v15, 0xe2, v212
	v_add_f32_e32 v112, v218, v14
	v_cndmask_b32_e32 v82, v203, v114, vcc
	v_cmp_le_i32_e32 vcc, v15, v213
	v_add_u32_e32 v15, 0xc3, v212
	s_nop 0
	v_cndmask_b32_e32 v66, v203, v66, vcc
	v_cmp_le_i32_e32 vcc, v15, v213
	v_add_u32_e32 v15, 0xe3, v212
	s_nop 0
	v_cndmask_b32_e32 v83, v203, v115, vcc
	v_cmp_le_i32_e32 vcc, v15, v213
	v_add_u32_e32 v15, 0xc8, v212
	s_nop 0
	v_cndmask_b32_e32 v67, v203, v67, vcc
	v_cmp_le_i32_e32 vcc, v15, v213
	v_add_u32_e32 v15, 0xe8, v212
	s_nop 0
	v_cndmask_b32_e32 v84, v203, v116, vcc
	v_cmp_le_i32_e32 vcc, v15, v213
	v_add_u32_e32 v15, 0xc9, v212
	s_nop 0
	v_cndmask_b32_e32 v68, v203, v68, vcc
	v_cmp_le_i32_e32 vcc, v15, v213
	v_add_u32_e32 v15, 0xe9, v212
	s_nop 0
	v_cndmask_b32_e32 v85, v203, v117, vcc
	v_cmp_le_i32_e32 vcc, v15, v213
	v_add_u32_e32 v15, 0xca, v212
	s_nop 0
	v_cndmask_b32_e32 v69, v203, v69, vcc
	v_cmp_le_i32_e32 vcc, v15, v213
	v_add_u32_e32 v15, 0xea, v212
	s_nop 0
	v_cndmask_b32_e32 v86, v203, v118, vcc
	v_cmp_le_i32_e32 vcc, v15, v213
	v_add_u32_e32 v15, 0xcb, v212
	s_nop 0
	v_cndmask_b32_e32 v70, v203, v70, vcc
	v_cmp_le_i32_e32 vcc, v15, v213
	v_add_u32_e32 v15, 0xeb, v212
	s_nop 0
	v_cndmask_b32_e32 v87, v203, v119, vcc
	v_cmp_le_i32_e32 vcc, v15, v213
	v_add_u32_e32 v15, 0xd0, v212
	s_nop 0
	v_cndmask_b32_e32 v71, v203, v71, vcc
	v_cmp_le_i32_e32 vcc, v15, v213
	v_add_u32_e32 v15, 0xf0, v212
	s_nop 0
	v_cndmask_b32_e32 v88, v203, v120, vcc
	v_cmp_le_i32_e32 vcc, v15, v213
	v_add_u32_e32 v15, 0xd1, v212
	s_nop 0
	v_cndmask_b32_e32 v72, v203, v72, vcc
	v_cmp_le_i32_e32 vcc, v15, v213
	v_add_u32_e32 v15, 0xf1, v212
	s_nop 0
	v_cndmask_b32_e32 v89, v203, v121, vcc
	v_cmp_le_i32_e32 vcc, v15, v213
	v_add_u32_e32 v15, 0xd2, v212
	s_nop 0
	v_cndmask_b32_e32 v73, v203, v73, vcc
	v_cmp_le_i32_e32 vcc, v15, v213
	v_add_u32_e32 v15, 0xf2, v212
	s_nop 0
	v_cndmask_b32_e32 v90, v203, v122, vcc
	v_cmp_le_i32_e32 vcc, v15, v213
	v_add_u32_e32 v15, 0xd3, v212
	s_nop 0
	v_cndmask_b32_e32 v74, v203, v74, vcc
	v_cmp_le_i32_e32 vcc, v15, v213
	v_add_u32_e32 v15, 0xf3, v212
	s_nop 0
	v_cndmask_b32_e32 v91, v203, v123, vcc
	v_cmp_le_i32_e32 vcc, v15, v213
	v_add_u32_e32 v15, 0xd8, v212
	s_nop 0
	v_cndmask_b32_e32 v75, v203, v75, vcc
	v_cmp_le_i32_e32 vcc, v15, v213
	v_add_u32_e32 v15, 0xf8, v212
	s_nop 0
	v_cndmask_b32_e32 v92, v203, v124, vcc
	v_cmp_le_i32_e32 vcc, v15, v213
	v_add_u32_e32 v15, 0xd9, v212
	s_nop 0
	v_cndmask_b32_e32 v76, v203, v76, vcc
	v_cmp_le_i32_e32 vcc, v15, v213
	v_add_u32_e32 v15, 0xf9, v212
	s_nop 0
	v_cndmask_b32_e32 v93, v203, v125, vcc
	v_cmp_le_i32_e32 vcc, v15, v213
	v_add_u32_e32 v15, 0xda, v212
	s_nop 0
	v_cndmask_b32_e32 v77, v203, v77, vcc
	v_cmp_le_i32_e32 vcc, v15, v213
	v_add_u32_e32 v15, 0xfa, v212
	s_nop 0
	v_cndmask_b32_e32 v94, v203, v126, vcc
	v_cmp_le_i32_e32 vcc, v15, v213
	v_add_u32_e32 v15, 0xdb, v212
	s_nop 0
	v_cndmask_b32_e32 v78, v203, v78, vcc
	v_cmp_le_i32_e32 vcc, v15, v213
	v_add_u32_e32 v15, 0xfb, v212
	s_nop 0
	v_cndmask_b32_e32 v95, v203, v127, vcc
	v_cmp_le_i32_e32 vcc, v15, v213
	v_max_f32_e32 v15, v81, v81
	v_max_f32_e32 v15, v96, v15
	v_max3_f32 v96, v82, v83, v65
	v_max3_f32 v15, v15, v64, v66
	v_max3_f32 v15, v15, v67, v84
	v_max3_f32 v96, v96, v86, v87
	v_max3_f32 v15, v15, v85, v68
	v_max3_f32 v96, v96, v70, v71
	v_max3_f32 v15, v15, v69, v88
	v_max3_f32 v96, v96, v90, v91
	v_max3_f32 v15, v15, v89, v72
	v_max3_f32 v96, v96, v74, v75
	v_cndmask_b32_e32 v79, v203, v79, vcc
	v_max3_f32 v15, v15, v73, v92
	v_max3_f32 v96, v96, v94, v95
	v_max3_f32 v15, v15, v93, v76
	v_max3_f32 v96, v96, v78, v79
	v_max3_f32 v14, v15, v77, v96
	v_mov_b32_e32 v15, v14
	s_nop 1
	v_permlane32_swap_b32_e32 v14, v15
	v_max_f32_e32 v15, v15, v15
	v_max_f32_e32 v14, v14, v14
	v_max_f32_e32 v14, v14, v15
	v_cmp_lt_f32_e32 vcc, s94, v14
	s_cmp_lg_u64 vcc, 0
	s_cselect_b64 s[4:5], -1, 0
	s_cbranch_vccnz .LBB0_905
